# S5: U rows prefetched 7 chunks ahead via per-wave LDS ring filled by LDS-DMA; d-skip operands read from the ring
# speedup vs baseline: 1.0093x; 1.0029x over previous
.LBB0_895:
	s_andn2_b64 vcc, exec, s[4:5]
	s_cbranch_vccnz .LBB0_925
	v_readlane_b32 s4, v254, 28
	v_readlane_b32 s5, v254, 29
	s_mov_b32 s5, s29
	s_lshl_b64 s[2:3], s[4:5], 16
	s_waitcnt lgkmcnt(0)
	s_add_u32 s2, s82, s2
	s_addc_u32 s3, s83, s3
	s_add_u32 s8, s2, 0x8340000
	s_addc_u32 s9, s3, 0
	v_mov_b32_e32 v126, v247
	s_lshl_b64 s[6:7], s[4:5], 19
	s_add_u32 s2, s82, s6
	v_bfe_u32 v127, v126, 5, 1
	v_readfirstlane_b32 s10, v126
	s_addc_u32 s3, s83, s7
	v_lshlrev_b32_e32 v208, 4, v127
	s_mov_b32 s20, s4
	s_ashr_i32 s4, s10, 8
	v_lshl_add_u64 v[0:1], s[2:3], 0, v[208:209]
	v_readlane_b32 s2, v253, 61
	s_add_i32 s4, s2, s4
	s_and_b32 s13, s4, 0x7f
	s_waitcnt vmcnt(0)
	v_and_b32_e32 v134, 31, v126
	s_lshl_b32 s14, s13, 7
	v_or_b32_e32 v2, s14, v134
	v_and_b32_e32 v128, 63, v126
	s_lshl_b32 s2, s13, 9
	v_lshlrev_b32_e32 v2, 5, v2
	v_mov_b32_e32 v3, v209
	v_lshl_or_b32 v4, v128, 3, s2
	v_lshl_add_u64 v[0:1], v[0:1], 0, v[2:3]
	s_mov_b64 s[2:3], 0x8360000
	v_lshl_add_u64 v[2:3], v[0:1], 0, s[2:3]
	v_add_co_u32_e32 v0, vcc, 0x8360000, v0
	s_ashr_i32 s11, s10, 6
	s_nop 0
	v_addc_co_u32_e32 v1, vcc, 0, v1, vcc
	global_load_dwordx4 v[64:67], v[0:1], off
	global_load_dwordx2 v[124:125], v4, s[8:9]
	global_load_dwordx4 v[68:71], v[2:3], off offset:1024
	global_load_dwordx4 v[72:75], v[2:3], off offset:2048
	global_load_dwordx4 v[76:79], v[2:3], off offset:3072
	s_ashr_i32 s2, s4, 7
	s_and_b32 s12, s11, 3
	s_ashr_i32 s3, s2, 31
	s_lshl_b64 s[2:3], s[2:3], 23
	s_lshl_b32 s4, s12, 21
	s_or_b32 s4, s2, s4
	s_add_u32 s4, s82, s4
	s_addc_u32 s5, s83, s3
	s_lshl_b32 s15, s13, 5
	s_add_u32 s4, s4, s15
	s_addc_u32 s5, s5, 0
	s_add_u32 s4, s4, 0xa800000
	v_lshlrev_b32_e32 v0, 3, v127
	s_addc_u32 s5, s5, 0
	v_lshlrev_b32_e32 v132, 11, v134
	v_and_b32_e32 v2, 32, v126
	s_cmp_eq_u32 s12, 3
	v_mov_b32_e32 v1, 0
	v_lshlrev_b32_e32 v122, 1, v132
	v_lshlrev_b32_e32 v120, 1, v0
	v_lshrrev_b32_e32 v135, 1, v2
	v_mov_b32_e32 v0, 0
	s_mul_i32 s100, s11, 0x4200
	v_add_u32_e32 v174, v122, v120
	v_lshl_add_u32 v175, v128, 4, s100
	v_lshlrev_b32_e32 v176, 4, v134
	v_lshl_add_u32 v176, v127, 3, v176
	v_add_u32_e32 v176, s100, v176
	s_cbranch_scc1 .LBB0_900
	v_lshlrev_b32_e32 v0, 3, v134
	v_mov_b32_e32 v1, v209
	v_lshl_add_u64 v[0:1], s[8:9], 0, v[0:1]
	s_lshl_b32 s28, s14, 2
	v_lshl_add_u64 v[0:1], v[0:1], 0, s[28:29]
	global_load_dwordx2 v[2:3], v[0:1], off
	v_cmp_gt_u32_e32 vcc, 32, v128
	global_load_dwordx2 v[0:1], v[0:1], off offset:256
	v_mov_b32_e32 v123, v209
	v_mov_b32_e32 v121, v209
	s_lshl_b32 s9, s10, 15
	s_and_b32 s9, s9, 0x600000
	s_or_b32 s9, s2, s9
	s_lshr_b32 s8, s10, 8
	v_mov_b32_e32 v84, 0
	v_mov_b32_e32 v94, v84
	v_mov_b32_e32 v95, v84
	s_waitcnt vmcnt(1)
	v_fmamk_f32 v4, v3, 0x80000000, v2
	v_fma_f32 v5, 0, v2, v3
	v_mul_f32_e32 v6, v3, v4
	v_mul_f32_e32 v7, v3, v5
	v_fmac_f32_e32 v6, v2, v5
	v_fma_f32 v7, v2, v4, -v7
	v_mul_f32_e32 v9, v2, v6
	v_mul_f32_e32 v8, v3, v6
	v_fmac_f32_e32 v9, v3, v7
	v_fma_f32 v11, v2, v7, -v8
	v_mul_f32_e32 v8, v2, v9
	v_mul_f32_e32 v10, v3, v9
	v_fmac_f32_e32 v8, v3, v11
	v_fma_f32 v10, v2, v11, -v10
	v_mul_f32_e32 v12, v2, v8
	v_mul_f32_e32 v13, v3, v8
	v_fmac_f32_e32 v12, v3, v10
	v_fma_f32 v13, v2, v10, -v13
	v_mul_f32_e32 v14, v2, v12
	v_mul_f32_e32 v15, v3, v12
	v_fmac_f32_e32 v14, v3, v13
	v_fma_f32 v15, v2, v13, -v15
	v_mul_f32_e32 v16, v2, v14
	v_mul_f32_e32 v17, v3, v14
	v_fmac_f32_e32 v16, v3, v15
	v_fma_f32 v17, v2, v15, -v17
	v_mul_f32_e32 v18, v2, v16
	v_mul_f32_e32 v19, v3, v16
	v_fmac_f32_e32 v18, v3, v17
	v_fma_f32 v19, v2, v17, -v19
	v_mul_f32_e32 v20, v2, v18
	v_mul_f32_e32 v21, v3, v18
	v_fmac_f32_e32 v20, v3, v19
	v_fma_f32 v21, v2, v19, -v21
	v_mul_f32_e32 v22, v2, v20
	v_mul_f32_e32 v23, v3, v20
	v_fmac_f32_e32 v22, v3, v21
	v_fma_f32 v23, v2, v21, -v23
	v_mul_f32_e32 v25, v2, v22
	v_mul_f32_e32 v24, v3, v22
	v_fmac_f32_e32 v25, v3, v23
	v_fma_f32 v27, v2, v23, -v24
	v_mul_f32_e32 v24, v2, v25
	v_mul_f32_e32 v26, v3, v25
	v_fmac_f32_e32 v24, v3, v27
	v_fma_f32 v26, v2, v27, -v26
	v_mul_f32_e32 v28, v2, v24
	v_mul_f32_e32 v29, v3, v24
	v_fmac_f32_e32 v28, v3, v26
	v_fma_f32 v29, v2, v26, -v29
	v_mul_f32_e32 v30, v2, v28
	v_mul_f32_e32 v31, v3, v28
	v_fmac_f32_e32 v30, v3, v29
	v_fma_f32 v31, v2, v29, -v31
	v_mul_f32_e32 v32, v2, v30
	v_mul_f32_e32 v33, v3, v30
	v_fmac_f32_e32 v32, v3, v31
	v_fma_f32 v33, v2, v31, -v33
	v_mul_f32_e32 v34, v2, v32
	v_mul_f32_e32 v35, v3, v32
	v_fmac_f32_e32 v34, v3, v33
	v_fma_f32 v35, v2, v33, -v35
	v_mul_f32_e32 v36, v2, v34
	v_mul_f32_e32 v37, v3, v34
	v_fmac_f32_e32 v36, v3, v35
	v_fma_f32 v37, v2, v35, -v37
	v_mul_f32_e32 v38, v2, v36
	v_mul_f32_e32 v39, v3, v36
	v_fmac_f32_e32 v38, v3, v37
	v_fma_f32 v39, v2, v37, -v39
	v_mul_f32_e32 v46, v2, v38
	v_mul_f32_e32 v40, v3, v38
	v_fmac_f32_e32 v46, v3, v39
	v_fma_f32 v47, v2, v39, -v40
	v_mul_f32_e32 v40, v2, v46
	v_mul_f32_e32 v41, v3, v46
	v_fmac_f32_e32 v40, v3, v47
	v_fma_f32 v41, v2, v47, -v41
	v_mul_f32_e32 v42, v2, v40
	v_mul_f32_e32 v43, v3, v40
	v_fmac_f32_e32 v42, v3, v41
	v_fma_f32 v43, v2, v41, -v43
	v_mul_f32_e32 v44, v2, v42
	v_mul_f32_e32 v45, v3, v42
	v_fmac_f32_e32 v44, v3, v43
	v_fma_f32 v45, v2, v43, -v45
	v_mul_f32_e32 v49, v2, v44
	v_mul_f32_e32 v48, v3, v44
	v_fmac_f32_e32 v49, v3, v45
	v_fma_f32 v48, v2, v45, -v48
	v_mul_f32_e32 v51, v2, v49
	v_mul_f32_e32 v50, v3, v49
	v_fmac_f32_e32 v51, v3, v48
	v_fma_f32 v50, v2, v48, -v50
	v_mul_f32_e32 v53, v2, v51
	v_mul_f32_e32 v52, v3, v51
	v_fmac_f32_e32 v53, v3, v50
	v_fma_f32 v52, v2, v50, -v52
	v_mul_f32_e32 v55, v2, v53
	v_mul_f32_e32 v54, v3, v53
	v_fmac_f32_e32 v55, v3, v52
	v_fma_f32 v54, v2, v52, -v54
	v_mul_f32_e32 v57, v2, v55
	v_mul_f32_e32 v56, v3, v55
	v_fmac_f32_e32 v57, v3, v54
	v_fma_f32 v56, v2, v54, -v56
	v_mul_f32_e32 v59, v2, v57
	v_mul_f32_e32 v58, v3, v57
	v_fmac_f32_e32 v59, v3, v56
	v_fma_f32 v58, v2, v56, -v58
	v_mul_f32_e32 v61, v2, v59
	v_mul_f32_e32 v60, v3, v59
	v_fmac_f32_e32 v61, v3, v58
	v_fma_f32 v60, v2, v58, -v60
	v_mul_f32_e32 v63, v2, v61
	v_mul_f32_e32 v62, v3, v61
	v_fmac_f32_e32 v63, v3, v60
	v_fma_f32 v62, v2, v60, -v62
	v_mul_f32_e32 v81, v2, v63
	v_mul_f32_e32 v80, v3, v63
	v_fmac_f32_e32 v81, v3, v62
	v_cndmask_b32_e32 v108, v4, v13, vcc
	s_waitcnt vmcnt(0)
	v_fmamk_f32 v4, v1, 0x80000000, v0
	v_fma_f32 v80, v2, v62, -v80
	v_mul_f32_e32 v82, v3, v81
	v_cndmask_b32_e32 v110, v7, v15, vcc
	v_cndmask_b32_e32 v109, v5, v12, vcc
	v_fma_f32 v5, 0, v0, v1
	v_mul_f32_e32 v7, v1, v4
	v_mul_f32_e32 v86, v2, v81
	v_fma_f32 v88, v2, v80, -v82
	v_mul_f32_e32 v2, v1, v5
	v_fmac_f32_e32 v7, v0, v5
	v_cndmask_b32_e32 v113, v9, v16, vcc
	v_cndmask_b32_e32 v111, v6, v14, vcc
	v_fma_f32 v6, v0, v4, -v2
	v_mul_f32_e32 v9, v0, v7
	v_mul_f32_e32 v2, v1, v7
	v_fmac_f32_e32 v9, v1, v6
	v_cndmask_b32_e32 v112, v11, v17, vcc
	v_cndmask_b32_e32 v107, 0, v8, vcc
	v_fma_f32 v8, v0, v6, -v2
	v_mul_f32_e32 v11, v0, v9
	v_mul_f32_e32 v2, v1, v9
	v_fmac_f32_e32 v11, v1, v8
	v_cndmask_b32_e32 v106, 1.0, v10, vcc
	v_fma_f32 v10, v0, v8, -v2
	v_mul_f32_e32 v13, v0, v11
	v_mul_f32_e32 v2, v1, v11
	v_fmac_f32_e32 v13, v1, v10
	v_fma_f32 v12, v0, v10, -v2
	v_mul_f32_e32 v15, v0, v13
	v_mul_f32_e32 v2, v1, v13
	v_fmac_f32_e32 v15, v1, v12
	v_fma_f32 v14, v0, v12, -v2
	v_mul_f32_e32 v17, v0, v15
	v_mul_f32_e32 v2, v1, v15
	v_fmac_f32_e32 v17, v1, v14
	v_cndmask_b32_e32 v114, v19, v26, vcc
	v_fma_f32 v16, v0, v14, -v2
	v_mul_f32_e32 v19, v0, v17
	v_mul_f32_e32 v2, v1, v17
	v_fmac_f32_e32 v19, v1, v16
	v_cndmask_b32_e32 v118, v21, v29, vcc
	v_cndmask_b32_e32 v116, v18, v24, vcc
	v_fma_f32 v18, v0, v16, -v2
	v_mul_f32_e32 v21, v0, v19
	v_mul_f32_e32 v2, v1, v19
	v_fmac_f32_e32 v21, v1, v18
	v_cndmask_b32_e32 v129, v23, v31, vcc
	v_cndmask_b32_e32 v119, v20, v28, vcc
	v_fma_f32 v20, v0, v18, -v2
	v_mul_f32_e32 v23, v0, v21
	v_mul_f32_e32 v2, v1, v21
	v_fmac_f32_e32 v23, v1, v20
	v_cndmask_b32_e32 v133, v25, v32, vcc
	v_cndmask_b32_e32 v130, v22, v30, vcc
	v_fma_f32 v22, v0, v20, -v2
	v_mul_f32_e32 v25, v0, v23
	v_mul_f32_e32 v2, v1, v23
	v_fmac_f32_e32 v25, v1, v22
	v_cndmask_b32_e32 v131, v27, v33, vcc
	v_fma_f32 v24, v0, v22, -v2
	v_mul_f32_e32 v27, v0, v25
	v_mul_f32_e32 v2, v1, v25
	v_fmac_f32_e32 v27, v1, v24
	v_fma_f32 v26, v0, v24, -v2
	v_mul_f32_e32 v29, v0, v27
	v_mul_f32_e32 v2, v1, v27
	v_fmac_f32_e32 v29, v1, v26
	v_fma_f32 v28, v0, v26, -v2
	v_mul_f32_e32 v31, v0, v29
	v_mul_f32_e32 v2, v1, v29
	v_fmac_f32_e32 v31, v1, v28
	v_fma_f32 v30, v0, v28, -v2
	v_mul_f32_e32 v33, v0, v31
	v_mul_f32_e32 v2, v1, v31
	v_fmac_f32_e32 v33, v1, v30
	v_cndmask_b32_e32 v136, v35, v41, vcc
	v_fma_f32 v32, v0, v30, -v2
	v_mul_f32_e32 v35, v0, v33
	v_mul_f32_e32 v2, v1, v33
	v_fmac_f32_e32 v35, v1, v32
	v_cndmask_b32_e32 v138, v37, v43, vcc
	v_cndmask_b32_e32 v137, v34, v40, vcc
	v_fma_f32 v34, v0, v32, -v2
	v_mul_f32_e32 v37, v0, v35
	v_mul_f32_e32 v2, v1, v35
	v_fmac_f32_e32 v37, v1, v34
	v_cndmask_b32_e32 v140, v39, v45, vcc
	v_cndmask_b32_e32 v139, v36, v42, vcc
	v_fma_f32 v36, v0, v34, -v2
	v_mul_f32_e32 v39, v0, v37
	v_mul_f32_e32 v2, v1, v37
	v_fmac_f32_e32 v39, v1, v36
	v_cndmask_b32_e32 v141, v38, v44, vcc
	v_fma_f32 v38, v0, v36, -v2
	v_mul_f32_e32 v41, v0, v39
	v_mul_f32_e32 v2, v1, v39
	v_fmac_f32_e32 v41, v1, v38
	v_fma_f32 v40, v0, v38, -v2
	v_mul_f32_e32 v43, v0, v41
	v_mul_f32_e32 v2, v1, v41
	v_fmac_f32_e32 v43, v1, v40
	v_fma_f32 v42, v0, v40, -v2
	v_mul_f32_e32 v45, v0, v43
	v_mul_f32_e32 v2, v1, v43
	v_fmac_f32_e32 v45, v1, v42
	v_cndmask_b32_e32 v115, v47, v48, vcc
	v_fma_f32 v44, v0, v42, -v2
	v_mul_f32_e32 v47, v0, v45
	v_mul_f32_e32 v2, v1, v45
	v_fmac_f32_e32 v47, v1, v44
	v_cndmask_b32_e32 v117, v46, v49, vcc
	v_fma_f32 v46, v0, v44, -v2
	v_mul_f32_e32 v49, v0, v47
	v_mul_f32_e32 v2, v1, v47
	v_fmac_f32_e32 v49, v1, v46
	v_cndmask_b32_e32 v99, v51, v59, vcc
	v_fma_f32 v48, v0, v46, -v2
	v_mul_f32_e32 v51, v0, v49
	v_mul_f32_e32 v2, v1, v49
	v_fmac_f32_e32 v51, v1, v48
	v_cndmask_b32_e32 v98, v50, v58, vcc
	v_fma_f32 v50, v0, v48, -v2
	v_mul_f32_e32 v2, v1, v51
	v_cndmask_b32_e32 v100, v52, v60, vcc
	v_fmac_f32_e32 v86, v3, v80
	v_fma_f32 v52, v0, v50, -v2
	v_lshl_add_u64 v[2:3], s[4:5], 0, v[122:123]
	v_lshl_add_u64 v[2:3], v[2:3], 0, v[120:121]
	v_cndmask_b32_e32 v104, v56, v80, vcc
	v_cndmask_b32_e32 v105, v57, v81, vcc
	s_mov_b64 s[98:99], s[4:5]
	s_add_i32 m0, s100, 0x0
	s_nop 0
	global_load_lds_dwordx4 v174, s[98:99]
	s_add_u32 s98, s98, 0x20000
	s_addc_u32 s99, s99, 0
	s_add_i32 m0, s100, 0x400
	s_nop 0
	global_load_lds_dwordx4 v174, s[98:99]
	s_add_u32 s98, s98, 0x20000
	s_addc_u32 s99, s99, 0
	s_add_i32 m0, s100, 0x800
	s_nop 0
	global_load_lds_dwordx4 v174, s[98:99]
	s_add_u32 s98, s98, 0x20000
	s_addc_u32 s99, s99, 0
	s_add_i32 m0, s100, 0xc00
	s_nop 0
	global_load_lds_dwordx4 v174, s[98:99]
	s_add_u32 s98, s98, 0x20000
	s_addc_u32 s99, s99, 0
	s_add_i32 m0, s100, 0x1000
	s_nop 0
	global_load_lds_dwordx4 v174, s[98:99]
	s_add_u32 s98, s98, 0x20000
	s_addc_u32 s99, s99, 0
	s_add_i32 m0, s100, 0x1400
	s_nop 0
	global_load_lds_dwordx4 v174, s[98:99]
	s_add_u32 s98, s98, 0x20000
	s_addc_u32 s99, s99, 0
	s_add_i32 m0, s100, 0x1800
	s_nop 0
	global_load_lds_dwordx4 v174, s[98:99]
	s_add_u32 s98, s98, 0x20000
	s_addc_u32 s99, s99, 0
	s_mov_b32 s101, 0
	v_cndmask_b32_e32 v101, v53, v61, vcc
	v_mul_f32_e32 v53, v0, v51
	v_fmac_f32_e32 v53, v1, v50
	v_mul_f32_e32 v3, v0, v53
	v_mul_f32_e32 v2, v1, v53
	v_fmac_f32_e32 v3, v1, v52
	v_cndmask_b32_e32 v103, v55, v63, vcc
	v_fma_f32 v2, v0, v52, -v2
	v_mul_f32_e32 v55, v0, v3
	v_cndmask_b32_e32 v102, v54, v62, vcc
	v_mul_f32_e32 v54, v1, v3
	v_fmac_f32_e32 v55, v1, v2
	v_fma_f32 v54, v0, v2, -v54
	v_mul_f32_e32 v57, v0, v55
	v_mul_f32_e32 v56, v1, v55
	v_fmac_f32_e32 v57, v1, v54
	v_fma_f32 v56, v0, v54, -v56
	v_mul_f32_e32 v59, v0, v57
	v_mul_f32_e32 v58, v1, v57
	v_fmac_f32_e32 v59, v1, v56
	v_fma_f32 v58, v0, v56, -v58
	v_mul_f32_e32 v61, v0, v59
	v_mul_f32_e32 v60, v1, v59
	v_fmac_f32_e32 v61, v1, v58
	v_fma_f32 v60, v0, v58, -v60
	v_mul_f32_e32 v63, v0, v61
	v_mul_f32_e32 v62, v1, v61
	v_fmac_f32_e32 v63, v1, v60
	v_fma_f32 v62, v0, v60, -v62
	v_mul_f32_e32 v85, v1, v63
	v_fma_f32 v90, v0, v62, -v85
	v_mul_f32_e32 v92, v0, v63
	v_lshl_or_b32 v0, v134, 12, s9
	v_readlane_b32 s9, v253, 8
	s_add_i32 s8, s9, s8
	s_and_b32 s8, s8, 0x7f
	s_lshl_b32 s8, s8, 5
	v_fmac_f32_e32 v92, v1, v62
	v_or3_b32 v0, v0, s8, v135
	v_mov_b32_e32 v1, s3
	v_lshl_add_u64 v[0:1], s[82:83], 0, v[0:1]
	s_mov_b64 s[8:9], 0xa820000
	v_cndmask_b32_e32 v170, v54, v62, vcc
	v_cndmask_b32_e32 v171, v55, v63, vcc
	v_cndmask_b32_e32 v168, v2, v60, vcc
	v_cndmask_b32_e32 v169, v3, v61, vcc
	v_cndmask_b32_e32 v166, v52, v58, vcc
	v_cndmask_b32_e32 v167, v53, v59, vcc
	v_cndmask_b32_e32 v164, v50, v56, vcc
	v_cndmask_b32_e32 v165, v51, v57, vcc
	v_cndmask_b32_e32 v162, v40, v48, vcc
	v_cndmask_b32_e32 v163, v41, v49, vcc
	v_cndmask_b32_e32 v160, v38, v46, vcc
	v_cndmask_b32_e32 v161, v39, v47, vcc
	v_cndmask_b32_e32 v158, v36, v44, vcc
	v_cndmask_b32_e32 v159, v37, v45, vcc
	v_cndmask_b32_e32 v156, v34, v42, vcc
	v_cndmask_b32_e32 v157, v35, v43, vcc
	v_cndmask_b32_e32 v154, v24, v32, vcc
	v_cndmask_b32_e32 v155, v25, v33, vcc
	v_cndmask_b32_e32 v152, v22, v30, vcc
	v_cndmask_b32_e32 v153, v23, v31, vcc
	v_cndmask_b32_e32 v150, v20, v28, vcc
	v_cndmask_b32_e32 v151, v21, v29, vcc
	v_cndmask_b32_e32 v148, v18, v26, vcc
	v_cndmask_b32_e32 v149, v19, v27, vcc
	v_cndmask_b32_e32 v146, v8, v16, vcc
	v_cndmask_b32_e32 v147, v9, v17, vcc
	v_cndmask_b32_e32 v144, v6, v14, vcc
	v_cndmask_b32_e32 v145, v7, v15, vcc
	v_cndmask_b32_e32 v142, v4, v12, vcc
	v_cndmask_b32_e32 v143, v5, v13, vcc
	v_cndmask_b32_e32 v121, 1.0, v10, vcc
	v_cndmask_b32_e32 v123, 0, v11, vcc
	v_xor_b32_e32 v87, 0x80000000, v86
	v_xor_b32_e32 v93, 0x80000000, v92
	v_mov_b32_e32 v89, v88
	v_mov_b32_e32 v91, v90
	v_lshl_add_u64 v[96:97], v[0:1], 0, s[8:9]
	s_mov_b64 s[8:9], 0
	v_mov_b32_e32 v85, v84
.LBB0_898:
	s_waitcnt vmcnt(6)
	v_add_u32_e32 v177, s101, v175
	ds_read_b128 v[16:19], v177
	s_add_i32 s8, s101, 0x1c00
	s_and_b32 s8, s8, 0x1c00
	s_add_i32 m0, s100, s8
	s_cmp_lt_u32 s9, 8
	global_load_lds_dwordx4 v174, s[98:99]
	s_cselect_b32 s8, 0x20000, 0
	s_add_u32 s98, s98, s8
	s_addc_u32 s99, s99, 0
	s_add_i32 s101, s101, 0x400
	s_and_b32 s101, s101, 0x1c00
	s_add_i32 s9, s9, 1
	s_waitcnt lgkmcnt(0)
	v_mfma_f32_32x32x16_bf16 v[48:63], v[16:19], v[72:75], 0
	s_cmp_lg_u32 s9, 16
	v_mfma_f32_32x32x16_bf16 v[32:47], v[16:19], v[64:67], 0
	s_nop 9
	v_fma_f32 v172, -v105, v48, 0
	v_mfma_f32_32x32x16_bf16 v[0:15], v[16:19], v[68:71], 0
	v_fmac_f32_e32 v172, v104, v32
	v_fma_f32 v32, v105, v32, 0
	v_fmac_f32_e32 v32, v104, v48
	v_fma_f32 v48, -v103, v49, v172
	v_fmac_f32_e32 v48, v102, v33
	v_fmac_f32_e32 v32, v103, v33
	v_fmac_f32_e32 v32, v102, v49
	v_mfma_f32_32x32x16_bf16 v[16:31], v[16:19], v[76:79], 0
	v_fma_f32 v33, -v101, v50, v48
	v_fmac_f32_e32 v33, v100, v34
	v_fmac_f32_e32 v32, v101, v34
	v_fmac_f32_e32 v32, v100, v50
	v_fma_f32 v33, -v99, v51, v33
	v_fmac_f32_e32 v33, v98, v35
	v_fmac_f32_e32 v32, v99, v35
	v_fmac_f32_e32 v32, v98, v51
	v_fma_f32 v33, -v117, v52, v33
	v_fmac_f32_e32 v33, v115, v36
	v_fmac_f32_e32 v32, v117, v36
	s_nop 0
	v_fma_f32 v36, -v171, v16, 0
	v_fmac_f32_e32 v36, v170, v0
	v_fma_f32 v0, v171, v0, 0
	v_fmac_f32_e32 v0, v170, v16
	v_fma_f32 v16, -v169, v17, v36
	v_fmac_f32_e32 v0, v169, v1
	v_fmac_f32_e32 v16, v168, v1
	v_fmac_f32_e32 v0, v168, v17
	v_fma_f32 v1, -v167, v18, v16
	v_fmac_f32_e32 v0, v167, v2
	v_fmac_f32_e32 v1, v166, v2
	v_fmac_f32_e32 v0, v166, v18
	v_fma_f32 v1, -v165, v19, v1
	v_fmac_f32_e32 v0, v165, v3
	v_fmac_f32_e32 v1, v164, v3
	v_fmac_f32_e32 v0, v164, v19
	v_fma_f32 v1, -v163, v20, v1
	v_fmac_f32_e32 v0, v163, v4
	v_fmac_f32_e32 v32, v115, v52
	v_fmac_f32_e32 v1, v162, v4
	v_fmac_f32_e32 v0, v162, v20
	v_fma_f32 v33, -v141, v53, v33
	v_fmac_f32_e32 v32, v141, v37
	v_fma_f32 v1, -v161, v21, v1
	v_fmac_f32_e32 v0, v161, v5
	v_fmac_f32_e32 v33, v140, v37
	v_fmac_f32_e32 v32, v140, v53
	v_fmac_f32_e32 v1, v160, v5
	v_fmac_f32_e32 v0, v160, v21
	v_fma_f32 v33, -v139, v54, v33
	v_fmac_f32_e32 v32, v139, v38
	v_fma_f32 v1, -v159, v22, v1
	v_fmac_f32_e32 v0, v159, v6
	v_fmac_f32_e32 v33, v138, v38
	v_fmac_f32_e32 v32, v138, v54
	v_fmac_f32_e32 v1, v158, v6
	v_fmac_f32_e32 v0, v158, v22
	v_fma_f32 v33, -v137, v55, v33
	v_fmac_f32_e32 v32, v137, v39
	v_fma_f32 v1, -v157, v23, v1
	v_fmac_f32_e32 v0, v157, v7
	v_fmac_f32_e32 v33, v136, v39
	v_fmac_f32_e32 v32, v136, v55
	v_fmac_f32_e32 v1, v156, v7
	v_fmac_f32_e32 v0, v156, v23
	v_fma_f32 v33, -v133, v56, v33
	v_fmac_f32_e32 v32, v133, v40
	v_fma_f32 v1, -v155, v24, v1
	v_fmac_f32_e32 v0, v155, v8
	v_fmac_f32_e32 v33, v131, v40
	v_fmac_f32_e32 v32, v131, v56
	v_fmac_f32_e32 v1, v154, v8
	v_fmac_f32_e32 v0, v154, v24
	v_fma_f32 v33, -v130, v57, v33
	v_fmac_f32_e32 v32, v130, v41
	v_fma_f32 v1, -v153, v25, v1
	v_fmac_f32_e32 v0, v153, v9
	v_fmac_f32_e32 v33, v129, v41
	v_fmac_f32_e32 v32, v129, v57
	v_fmac_f32_e32 v1, v152, v9
	v_fmac_f32_e32 v0, v152, v25
	v_fma_f32 v33, -v119, v58, v33
	v_fmac_f32_e32 v32, v119, v42
	v_fma_f32 v1, -v151, v26, v1
	v_fmac_f32_e32 v0, v151, v10
	v_fmac_f32_e32 v33, v118, v42
	v_fmac_f32_e32 v32, v118, v58
	v_fmac_f32_e32 v1, v150, v10
	v_fmac_f32_e32 v0, v150, v26
	v_fma_f32 v33, -v116, v59, v33
	v_fmac_f32_e32 v32, v116, v43
	v_fma_f32 v1, -v149, v27, v1
	v_fmac_f32_e32 v0, v149, v11
	v_fmac_f32_e32 v33, v114, v43
	v_fmac_f32_e32 v32, v114, v59
	v_fmac_f32_e32 v1, v148, v11
	v_fmac_f32_e32 v0, v148, v27
	v_fma_f32 v33, -v113, v60, v33
	v_fmac_f32_e32 v32, v113, v44
	v_fma_f32 v1, -v147, v28, v1
	v_fmac_f32_e32 v0, v147, v12
	v_fmac_f32_e32 v33, v112, v44
	v_fmac_f32_e32 v32, v112, v60
	v_fmac_f32_e32 v1, v146, v12
	v_fmac_f32_e32 v0, v146, v28
	v_fma_f32 v33, -v111, v61, v33
	v_fmac_f32_e32 v32, v111, v45
	v_fma_f32 v1, -v145, v29, v1
	v_fmac_f32_e32 v0, v145, v13
	v_fmac_f32_e32 v33, v110, v45
	v_fmac_f32_e32 v32, v110, v61
	v_fmac_f32_e32 v1, v144, v13
	v_fmac_f32_e32 v0, v144, v29
	v_fma_f32 v33, -v109, v62, v33
	v_fmac_f32_e32 v32, v109, v46
	v_fma_f32 v1, -v143, v30, v1
	v_fmac_f32_e32 v0, v143, v14
	v_fmac_f32_e32 v33, v108, v46
	v_fmac_f32_e32 v32, v108, v62
	v_fmac_f32_e32 v1, v142, v14
	v_fmac_f32_e32 v0, v142, v30
	v_fma_f32 v33, -v107, v63, v33
	v_fmac_f32_e32 v32, v107, v47
	v_fma_f32 v1, -v123, v31, v1
	v_fmac_f32_e32 v0, v123, v15
	v_fmac_f32_e32 v33, v106, v47
	v_fmac_f32_e32 v32, v106, v63
	v_fmac_f32_e32 v1, v121, v15
	v_fmac_f32_e32 v0, v121, v31
	v_mov_b32_e32 v35, v33
	v_mov_b32_e32 v34, v32
	v_mov_b32_e32 v3, v1
	v_mov_b32_e32 v2, v0
	v_permlane32_swap_b32_e32 v33, v35
	v_permlane32_swap_b32_e32 v32, v34
	v_permlane32_swap_b32_e32 v1, v3
	v_permlane32_swap_b32_e32 v0, v2
	v_pk_add_f32 v[4:5], v[32:33], v[34:35]
	v_pk_add_f32 v[0:1], v[0:1], v[2:3]
	v_pk_fma_f32 v[4:5], v[86:87], v[84:85], v[4:5] op_sel:[0,1,0] op_sel_hi:[1,0,1]
	v_pk_fma_f32 v[0:1], v[92:93], v[94:95], v[0:1] op_sel:[0,1,0] op_sel_hi:[1,0,1]
	v_pk_fma_f32 v[84:85], v[88:89], v[84:85], v[4:5]
	v_pk_fma_f32 v[94:95], v[90:91], v[94:95], v[0:1]
	s_cbranch_scc1 .LBB0_898
	v_cmp_gt_u32_e32 vcc, 32, v128
	s_nop 1
	v_cndmask_b32_e32 v0, v95, v85, vcc
	v_cndmask_b32_e32 v1, v94, v84, vcc

.LBB0_920:
	v_mov_b32_e32 v123, v209
	v_lshl_add_u64 v[2:3], s[4:5], 0, v[122:123]
	v_mov_b32_e32 v121, v209
	v_lshl_add_u64 v[2:3], v[2:3], 0, v[120:121]
	s_mov_b64 s[98:99], s[4:5]
	s_add_i32 m0, s100, 0x0
	s_nop 0
	global_load_lds_dwordx4 v174, s[98:99]
	s_add_u32 s98, s98, 0x20000
	s_addc_u32 s99, s99, 0
	s_add_i32 m0, s100, 0x400
	s_nop 0
	global_load_lds_dwordx4 v174, s[98:99]
	s_add_u32 s98, s98, 0x20000
	s_addc_u32 s99, s99, 0
	s_add_i32 m0, s100, 0x800
	s_nop 0
	global_load_lds_dwordx4 v174, s[98:99]
	s_add_u32 s98, s98, 0x20000
	s_addc_u32 s99, s99, 0
	s_add_i32 m0, s100, 0xc00
	s_nop 0
	global_load_lds_dwordx4 v174, s[98:99]
	s_add_u32 s98, s98, 0x20000
	s_addc_u32 s99, s99, 0
	s_add_i32 m0, s100, 0x1000
	s_nop 0
	global_load_lds_dwordx4 v174, s[98:99]
	s_add_u32 s98, s98, 0x20000
	s_addc_u32 s99, s99, 0
	s_add_i32 m0, s100, 0x1400
	s_nop 0
	global_load_lds_dwordx4 v174, s[98:99]
	s_add_u32 s98, s98, 0x20000
	s_addc_u32 s99, s99, 0
	s_add_i32 m0, s100, 0x1800
	s_nop 0
	global_load_lds_dwordx4 v174, s[98:99]
	s_add_u32 s98, s98, 0x20000
	s_addc_u32 s99, s99, 0
	s_mov_b32 s101, 0
	s_mulk_i32 s11, 0x4200
	s_add_i32 s4, s11, 0
	s_lshl_b32 s5, s10, 15
	v_mov_b32_e32 v3, s4
	v_lshl_add_u32 v4, v128, 6, s4
	v_lshl_add_u32 v5, v134, 6, s4
	s_movk_i32 s4, 0x110
	s_and_b32 s5, s5, 0x600000
	v_mad_u32_u24 v3, v134, s4, v3
	s_lshr_b32 s4, s10, 8
	s_or_b32 s2, s2, s5
	v_readlane_b32 s5, v253, 8
	s_add_i32 s4, s5, s4
	v_lshrrev_b32_e32 v1, 2, v126
	s_and_b32 s4, s4, 0x7f
	v_bfe_u32 v2, v126, 2, 2
	v_bitop3_b32 v1, v127, v1, 3 bitop3:0x78
	s_lshl_b32 s4, s4, 5
	v_lshlrev_b32_e32 v7, 4, v1
	v_bitop3_b32 v1, v127, v2, 2 bitop3:0x36
	s_or_b32 s2, s2, s4
	v_lshlrev_b32_e32 v0, 2, v127
	v_lshlrev_b32_e32 v2, 4, v1
	v_lshlrev_b32_e32 v1, 2, v126
	s_add_u32 s4, s82, s2
	v_and_b32_e32 v8, 48, v1
	v_bitop3_b32 v9, v1, 16, 48 bitop3:0x6c
	v_bitop3_b32 v10, v1, 32, 48 bitop3:0x6c
	v_bitop3_b32 v11, v1, 48, v1 bitop3:0xc
	v_add_lshl_u32 v0, v132, v0, 1
	v_mov_b32_e32 v1, v209
	s_addc_u32 s5, s83, s3
	v_lshl_add_u64 v[132:133], s[4:5], 0, v[0:1]
	v_lshlrev_b32_e32 v0, 12, v134
	v_or3_b32 v0, s2, v0, v135
	v_mov_b32_e32 v1, s3
	v_mul_i32_i24_e32 v6, 0xffffffc4, v128
	s_waitcnt vmcnt(6)
	v_xor_b32_e32 v126, 0x80000000, v125
	v_mov_b32_e32 v127, v125
	v_lshl_add_u64 v[0:1], s[82:83], 0, v[0:1]
	s_mov_b64 s[2:3], 0xa820000
	v_mov_b32_e32 v128, v124
	v_mov_b32_e32 v129, v124
	v_pk_mov_b32 v[130:131], v[126:127], v[126:127] op_sel:[1,0]
	v_lshl_add_u64 v[134:135], v[0:1], 0, s[2:3]
	s_mov_b64 s[2:3], 0
	v_add_u32_e32 v144, v5, v7
	v_add_u32_e32 v145, v5, v2
	v_add_u32_e32 v146, v4, v8
	v_add_u32_e32 v147, v4, v9
	v_add_u32_e32 v148, v4, v10
	v_add_u32_e32 v149, v4, v11
	v_add_u32_e32 v150, v4, v6
	v_add_u32_e32 v151, v3, v208
	s_waitcnt vmcnt(0)
	s_branch .LBB0_922
.LBB0_921:
	v_lshl_add_u64 v[136:137], v[132:133], 0, s[2:3]
	v_mfma_f32_32x32x16_bf16 v[32:47], v[48:51], v[64:67], 0
	s_mov_b32 s4, 0xc800000
	s_add_u32 s2, s2, 0x20000
	s_addc_u32 s3, s3, 0
	s_cmp_lg_u32 s2, 0x200000
	v_mfma_f32_32x32x16_bf16 v[16:31], v[48:51], v[68:71], 0
	v_mfma_f32_32x32x16_bf16 v[0:15], v[48:51], v[72:75], 0
	v_mfma_f32_32x32x16_bf16 v[48:63], v[48:51], v[76:79], 0
	s_nop 9
	v_permlane32_swap_b32_e32 v32, v16
	v_permlane32_swap_b32_e32 v33, v17
	v_permlane32_swap_b32_e32 v34, v18
	v_permlane32_swap_b32_e32 v35, v19
	v_permlane32_swap_b32_e32 v36, v20
	v_permlane32_swap_b32_e32 v37, v21
	v_permlane32_swap_b32_e32 v38, v22
	v_permlane32_swap_b32_e32 v39, v23
	v_permlane32_swap_b32_e32 v40, v24
	v_permlane32_swap_b32_e32 v41, v25
	v_permlane32_swap_b32_e32 v42, v26
	v_permlane32_swap_b32_e32 v43, v27
	v_permlane32_swap_b32_e32 v44, v28
	v_permlane32_swap_b32_e32 v45, v29
	v_permlane32_swap_b32_e32 v46, v30
	v_permlane32_swap_b32_e32 v47, v31
	v_permlane32_swap_b32_e32 v0, v48
	v_permlane32_swap_b32_e32 v1, v49
	v_permlane32_swap_b32_e32 v2, v50
	v_permlane32_swap_b32_e32 v3, v51
	v_permlane32_swap_b32_e32 v4, v52
	v_permlane32_swap_b32_e32 v5, v53
	v_permlane32_swap_b32_e32 v6, v54
	v_permlane32_swap_b32_e32 v7, v55
	v_permlane32_swap_b32_e32 v8, v56
	v_permlane32_swap_b32_e32 v9, v57
	v_permlane32_swap_b32_e32 v10, v58
	v_permlane32_swap_b32_e32 v11, v59
	v_permlane32_swap_b32_e32 v12, v60
	v_permlane32_swap_b32_e32 v13, v61
	v_permlane32_swap_b32_e32 v14, v62
	v_permlane32_swap_b32_e32 v15, v63
	v_fma_f32 v32, -v125, v142, v32
	v_fma_f32 v0, v125, v143, v0
	v_fmac_f32_e32 v32, v124, v143
	v_fmac_f32_e32 v0, v124, v142
	v_cvt_pk_bf16_f32 v154, v32, v0
	ds_write_b32 v150, v154 offset:8192
	v_fma_f32 v33, -v125, v0, v33
	v_fma_f32 v1, v125, v32, v1
	v_fmac_f32_e32 v33, v124, v32
	v_fmac_f32_e32 v1, v124, v0
	v_cvt_pk_bf16_f32 v154, v33, v1
	ds_write_b32 v150, v154 offset:8464
	v_fma_f32 v34, -v125, v1, v34
	v_fma_f32 v2, v125, v33, v2
	v_fmac_f32_e32 v34, v124, v33
	v_fmac_f32_e32 v2, v124, v1
	v_cvt_pk_bf16_f32 v154, v34, v2
	ds_write_b32 v150, v154 offset:8736
	v_fma_f32 v35, -v125, v2, v35
	v_fma_f32 v3, v125, v34, v3
	v_fmac_f32_e32 v35, v124, v34
	v_fmac_f32_e32 v3, v124, v2
	v_cvt_pk_bf16_f32 v154, v35, v3
	ds_write_b32 v150, v154 offset:9008
	v_fma_f32 v16, -v125, v3, v16
	v_fma_f32 v48, v125, v35, v48
	v_fmac_f32_e32 v16, v124, v35
	v_fmac_f32_e32 v48, v124, v3
	v_cvt_pk_bf16_f32 v154, v16, v48
	ds_write_b32 v150, v154 offset:9280
	v_fma_f32 v17, -v125, v48, v17
	v_fma_f32 v49, v125, v16, v49
	v_fmac_f32_e32 v17, v124, v16
	v_fmac_f32_e32 v49, v124, v48
	v_cvt_pk_bf16_f32 v154, v17, v49
	ds_write_b32 v150, v154 offset:9552
	v_fma_f32 v18, -v125, v49, v18
	v_fma_f32 v50, v125, v17, v50
	v_fmac_f32_e32 v18, v124, v17
	v_fmac_f32_e32 v50, v124, v49
	v_cvt_pk_bf16_f32 v154, v18, v50
	ds_write_b32 v150, v154 offset:9824
	v_fma_f32 v19, -v125, v50, v19
	v_fma_f32 v51, v125, v18, v51
	v_fmac_f32_e32 v19, v124, v18
	v_fmac_f32_e32 v51, v124, v50
	v_cvt_pk_bf16_f32 v154, v19, v51
	ds_write_b32 v150, v154 offset:10096
	v_fma_f32 v36, -v125, v51, v36
	v_fma_f32 v4, v125, v19, v4
	v_fmac_f32_e32 v36, v124, v19
	v_fmac_f32_e32 v4, v124, v51
	v_cvt_pk_bf16_f32 v154, v36, v4
	ds_write_b32 v150, v154 offset:10368
	v_fma_f32 v37, -v125, v4, v37
	v_fma_f32 v5, v125, v36, v5
	v_fmac_f32_e32 v37, v124, v36
	v_fmac_f32_e32 v5, v124, v4
	v_cvt_pk_bf16_f32 v154, v37, v5
	ds_write_b32 v150, v154 offset:10640
	v_fma_f32 v38, -v125, v5, v38
	v_fma_f32 v6, v125, v37, v6
	v_fmac_f32_e32 v38, v124, v37
	v_fmac_f32_e32 v6, v124, v5
	v_cvt_pk_bf16_f32 v154, v38, v6
	ds_write_b32 v150, v154 offset:10912
	v_fma_f32 v39, -v125, v6, v39
	v_fma_f32 v7, v125, v38, v7
	v_fmac_f32_e32 v39, v124, v38
	v_fmac_f32_e32 v7, v124, v6
	v_cvt_pk_bf16_f32 v154, v39, v7
	ds_write_b32 v150, v154 offset:11184
	v_fma_f32 v20, -v125, v7, v20
	v_fma_f32 v52, v125, v39, v52
	v_fmac_f32_e32 v20, v124, v39
	v_fmac_f32_e32 v52, v124, v7
	v_cvt_pk_bf16_f32 v154, v20, v52
	ds_write_b32 v150, v154 offset:11456
	v_fma_f32 v21, -v125, v52, v21
	v_fma_f32 v53, v125, v20, v53
	v_fmac_f32_e32 v21, v124, v20
	v_fmac_f32_e32 v53, v124, v52
	v_cvt_pk_bf16_f32 v154, v21, v53
	ds_write_b32 v150, v154 offset:11728
	v_fma_f32 v22, -v125, v53, v22
	v_fma_f32 v54, v125, v21, v54
	v_fmac_f32_e32 v22, v124, v21
	v_fmac_f32_e32 v54, v124, v53
	v_cvt_pk_bf16_f32 v154, v22, v54
	ds_write_b32 v150, v154 offset:12000
	v_fma_f32 v23, -v125, v54, v23
	v_fma_f32 v55, v125, v22, v55
	v_fmac_f32_e32 v23, v124, v22
	v_fmac_f32_e32 v55, v124, v54
	v_cvt_pk_bf16_f32 v154, v23, v55
	ds_write_b32 v150, v154 offset:12272
	v_fma_f32 v40, -v125, v55, v40
	v_fma_f32 v8, v125, v23, v8
	v_fmac_f32_e32 v40, v124, v23
	v_fmac_f32_e32 v8, v124, v55
	v_cvt_pk_bf16_f32 v154, v40, v8
	ds_write_b32 v150, v154 offset:12544
	v_fma_f32 v41, -v125, v8, v41
	v_fma_f32 v9, v125, v40, v9
	v_fmac_f32_e32 v41, v124, v40
	v_fmac_f32_e32 v9, v124, v8
	v_cvt_pk_bf16_f32 v154, v41, v9
	ds_write_b32 v150, v154 offset:12816
	v_fma_f32 v42, -v125, v9, v42
	v_fma_f32 v10, v125, v41, v10
	v_fmac_f32_e32 v42, v124, v41
	v_fmac_f32_e32 v10, v124, v9
	v_cvt_pk_bf16_f32 v154, v42, v10
	ds_write_b32 v150, v154 offset:13088
	v_fma_f32 v43, -v125, v10, v43
	v_fma_f32 v11, v125, v42, v11
	v_fmac_f32_e32 v43, v124, v42
	v_fmac_f32_e32 v11, v124, v10
	v_cvt_pk_bf16_f32 v154, v43, v11
	ds_write_b32 v150, v154 offset:13360
	v_fma_f32 v24, -v125, v11, v24
	v_fma_f32 v56, v125, v43, v56
	v_fmac_f32_e32 v24, v124, v43
	v_fmac_f32_e32 v56, v124, v11
	v_cvt_pk_bf16_f32 v154, v24, v56
	ds_write_b32 v150, v154 offset:13632
	v_fma_f32 v25, -v125, v56, v25
	v_fma_f32 v57, v125, v24, v57
	v_fmac_f32_e32 v25, v124, v24
	v_fmac_f32_e32 v57, v124, v56
	v_cvt_pk_bf16_f32 v154, v25, v57
	ds_write_b32 v150, v154 offset:13904
	v_fma_f32 v26, -v125, v57, v26
	v_fma_f32 v58, v125, v25, v58
	v_fmac_f32_e32 v26, v124, v25
	v_fmac_f32_e32 v58, v124, v57
	v_cvt_pk_bf16_f32 v154, v26, v58
	ds_write_b32 v150, v154 offset:14176
	v_fma_f32 v27, -v125, v58, v27
	v_fma_f32 v59, v125, v26, v59
	v_fmac_f32_e32 v27, v124, v26
	v_fmac_f32_e32 v59, v124, v58
	v_cvt_pk_bf16_f32 v154, v27, v59
	ds_write_b32 v150, v154 offset:14448
	v_fma_f32 v44, -v125, v59, v44
	v_fma_f32 v12, v125, v27, v12
	v_fmac_f32_e32 v44, v124, v27
	v_fmac_f32_e32 v12, v124, v59
	v_cvt_pk_bf16_f32 v154, v44, v12
	ds_write_b32 v150, v154 offset:14720
	v_fma_f32 v45, -v125, v12, v45
	v_fma_f32 v13, v125, v44, v13
	v_fmac_f32_e32 v45, v124, v44
	v_fmac_f32_e32 v13, v124, v12
	v_cvt_pk_bf16_f32 v154, v45, v13
	ds_write_b32 v150, v154 offset:14992
	v_fma_f32 v46, -v125, v13, v46
	v_fma_f32 v14, v125, v45, v14
	v_fmac_f32_e32 v46, v124, v45
	v_fmac_f32_e32 v14, v124, v13
	v_cvt_pk_bf16_f32 v154, v46, v14
	ds_write_b32 v150, v154 offset:15264
	v_fma_f32 v47, -v125, v14, v47
	v_fma_f32 v15, v125, v46, v15
	v_fmac_f32_e32 v47, v124, v46
	v_fmac_f32_e32 v15, v124, v14
	v_cvt_pk_bf16_f32 v154, v47, v15
	ds_write_b32 v150, v154 offset:15536
	v_fma_f32 v28, -v125, v15, v28
	v_fma_f32 v60, v125, v47, v60
	v_fmac_f32_e32 v28, v124, v47
	v_fmac_f32_e32 v60, v124, v15
	v_cvt_pk_bf16_f32 v154, v28, v60
	ds_write_b32 v150, v154 offset:15808
	v_fma_f32 v29, -v125, v60, v29
	v_fma_f32 v61, v125, v28, v61
	v_fmac_f32_e32 v29, v124, v28
	v_fmac_f32_e32 v61, v124, v60
	v_cvt_pk_bf16_f32 v154, v29, v61
	ds_write_b32 v150, v154 offset:16080
	v_fma_f32 v30, -v125, v61, v30
	v_fma_f32 v62, v125, v29, v62
	v_fmac_f32_e32 v30, v124, v29
	v_fmac_f32_e32 v62, v124, v61
	v_cvt_pk_bf16_f32 v154, v30, v62
	ds_write_b32 v150, v154 offset:16352
	v_fma_f32 v143, -v125, v62, v31
	v_fma_f32 v142, v125, v30, v63
	v_fmac_f32_e32 v143, v124, v30
	v_fmac_f32_e32 v142, v124, v62
	v_cvt_pk_bf16_f32 v154, v143, v142
	ds_write_b32 v150, v154 offset:16624
	ds_read_b128 v[0:3], v151 offset:8192
	ds_read_b128 v[16:19], v151 offset:8224
	s_waitcnt lgkmcnt(1)
	v_mfma_f32_32x32x16_bf16 v[0:15], v[84:87], v[0:3], 0
	s_waitcnt lgkmcnt(0)
	v_mfma_f32_32x32x16_bf16 v[0:15], v[80:83], v[16:19], v[0:15]
	ds_read_b128 v[16:19], v151 offset:8256
	ds_read_b128 v[20:23], v151 offset:8288
	s_waitcnt lgkmcnt(1)
	v_mfma_f32_32x32x16_bf16 v[0:15], v[88:91], v[16:19], v[0:15]
	s_waitcnt lgkmcnt(0)
	v_mfma_f32_32x32x16_bf16 v[0:15], v[92:95], v[20:23], v[0:15]
	ds_read_b128 v[16:19], v151 offset:8320
	ds_read_b128 v[20:23], v151 offset:8352
	s_waitcnt lgkmcnt(1)
	v_mfma_f32_32x32x16_bf16 v[0:15], v[96:99], v[16:19], v[0:15]
	s_waitcnt lgkmcnt(0)
	v_mfma_f32_32x32x16_bf16 v[0:15], v[100:103], v[20:23], v[0:15]
	ds_read_b128 v[16:19], v151 offset:8384
	ds_read_b128 v[20:23], v151 offset:8416
	s_waitcnt lgkmcnt(1)
	v_mfma_f32_32x32x16_bf16 v[0:15], v[104:107], v[16:19], v[0:15]
	s_waitcnt lgkmcnt(0)
	v_mfma_f32_32x32x16_bf16 v[0:15], v[108:111], v[20:23], v[0:15]
	s_nop 10
	v_and_b32_e32 v9, 0xffff0000, v140
	v_lshlrev_b32_e32 v10, 16, v141
	v_fma_f32 v1, v113, v9, v1
	v_fma_f32 v2, v114, v10, v2
	v_mul_f32_e32 v9, v1, v1
	v_mul_f32_e32 v10, v2, v2
	v_fmamk_f32 v9, v9, 0xbdd2d3e8, v246
	v_fmamk_f32 v10, v10, 0xbdd2d3e8, v246
	v_lshlrev_b32_e32 v8, 16, v140
	v_mul_f32_e32 v9, v1, v9
	v_mul_f32_e32 v10, v2, v10
	v_fma_f32 v0, v112, v8, v0
	v_exp_f32_e32 v9, v9
	v_exp_f32_e32 v10, v10
	v_mul_f32_e32 v8, v0, v0
	v_fmamk_f32 v8, v8, 0xbdd2d3e8, v246
	v_mul_f32_e32 v8, v0, v8
	v_exp_f32_e32 v8, v8
	v_add_f32_e32 v9, 1.0, v9
	v_add_f32_e32 v10, 1.0, v10
	v_and_b32_e32 v11, 0xffff0000, v141
	v_rcp_f32_e32 v9, v9
	v_rcp_f32_e32 v10, v10
	v_fma_f32 v3, v115, v11, v3
	v_mul_f32_e32 v11, v3, v3
	v_fmamk_f32 v11, v11, 0xbdd2d3e8, v246
	v_add_f32_e32 v8, 1.0, v8
	v_mul_f32_e32 v11, v3, v11
	v_rcp_f32_e32 v8, v8
	v_exp_f32_e32 v11, v11
	v_mul_f32_e32 v1, v1, v9
	v_mul_f32_e32 v2, v2, v10
	v_lshlrev_b32_e32 v9, 16, v138
	v_and_b32_e32 v10, 0xffff0000, v138
	v_fma_f32 v4, v116, v9, v4
	v_fma_f32 v5, v117, v10, v5
	v_mul_f32_e32 v9, v4, v4
	v_mul_f32_e32 v10, v5, v5
	v_fmamk_f32 v9, v9, 0xbdd2d3e8, v246
	v_fmamk_f32 v10, v10, 0xbdd2d3e8, v246
	v_mul_f32_e32 v0, v0, v8
	v_add_f32_e32 v8, 1.0, v11
	v_mul_f32_e32 v9, v4, v9
	v_mul_f32_e32 v10, v5, v10
	v_rcp_f32_e32 v8, v8
	v_exp_f32_e32 v9, v9
	v_exp_f32_e32 v10, v10
	v_and_b32_e32 v11, 0xffff0000, v139
	v_mul_f32_e32 v3, v3, v8
	v_add_f32_e32 v8, 1.0, v9
	v_add_f32_e32 v9, 1.0, v10
	v_lshlrev_b32_e32 v10, 16, v139
	v_fma_f32 v6, v118, v10, v6
	v_fmac_f32_e32 v7, v119, v11
	v_mul_f32_e32 v10, v6, v6
	v_mul_f32_e32 v11, v7, v7
	v_fmamk_f32 v10, v10, 0xbdd2d3e8, v246
	v_fmamk_f32 v11, v11, 0xbdd2d3e8, v246
	v_mul_f32_e32 v10, v6, v10
	v_mul_f32_e32 v11, v7, v11
	v_exp_f32_e32 v10, v10
	v_exp_f32_e32 v11, v11
	v_rcp_f32_e32 v8, v8
	v_rcp_f32_e32 v9, v9
	v_add_f32_e32 v10, 1.0, v10
	v_add_f32_e32 v11, 1.0, v11
	v_rcp_f32_e32 v10, v10
	v_rcp_f32_e32 v11, v11
	v_cvt_pk_bf16_f32 v0, v0, v1
	v_cvt_pk_bf16_f32 v1, v2, v3
	v_add_co_u32_e32 v2, vcc, s4, v136
	v_mul_f32_e32 v4, v4, v8
	s_nop 0
	v_addc_co_u32_e32 v3, vcc, 0, v137, vcc
	v_mul_f32_e32 v5, v5, v9
	v_mul_f32_e32 v6, v6, v10
	v_mul_f32_e32 v7, v7, v11
	global_store_dwordx2 v[2:3], v[0:1], off
	v_cvt_pk_bf16_f32 v0, v4, v5
	v_cvt_pk_bf16_f32 v1, v6, v7
	global_store_dwordx2 v[2:3], v[0:1], off offset:16
	s_cbranch_scc0 .LBB0_924
.LBB0_922:
	s_waitcnt vmcnt(20)
	v_add_u32_e32 v177, s101, v175
	v_add_u32_e32 v178, s101, v176
	ds_read_b128 v[48:51], v177
	ds_read2_b64 v[138:141], v178 offset0:64 offset1:0
	s_add_i32 s5, s101, 0x1c00
	s_and_b32 s5, s5, 0x1c00
	s_add_i32 m0, s100, s5
	s_cmp_lt_u32 s2, 0x100000
	global_load_lds_dwordx4 v174, s[98:99]
	s_cselect_b32 s5, 0x20000, 0
	s_add_u32 s98, s98, s5
	s_addc_u32 s99, s99, 0
	s_add_i32 s101, s101, 0x400
	s_and_b32 s101, s101, 0x1c00
	s_waitcnt lgkmcnt(0)
	s_branch .LBB0_921

	.amdhsa_kernel _ZN2mk4megaENS_6ParamsE
		.amdhsa_group_segment_fixed_size 0
		.amdhsa_private_segment_fixed_size 0
		.amdhsa_kernarg_size 448
		.amdhsa_user_sgpr_count 2
		.amdhsa_user_sgpr_dispatch_ptr 0
		.amdhsa_user_sgpr_queue_ptr 0
		.amdhsa_user_sgpr_kernarg_segment_ptr 1
		.amdhsa_user_sgpr_dispatch_id 0
		.amdhsa_user_sgpr_kernarg_preload_length 0
		.amdhsa_user_sgpr_kernarg_preload_offset 0
		.amdhsa_user_sgpr_private_segment_size 0
		.amdhsa_uses_dynamic_stack 0
		.amdhsa_enable_private_segment 0
		.amdhsa_system_sgpr_workgroup_id_x 1
		.amdhsa_system_sgpr_workgroup_id_y 0
		.amdhsa_system_sgpr_workgroup_id_z 0
		.amdhsa_system_sgpr_workgroup_info 0
		.amdhsa_system_vgpr_workitem_id 2
		.amdhsa_next_free_vgpr 256
		.amdhsa_next_free_sgpr 102
		.amdhsa_accum_offset 256
		.amdhsa_reserve_vcc 1
		.amdhsa_float_round_mode_32 0
		.amdhsa_float_round_mode_16_64 0
		.amdhsa_float_denorm_mode_32 3
		.amdhsa_float_denorm_mode_16_64 3
		.amdhsa_dx10_clamp 1
		.amdhsa_ieee_mode 1
		.amdhsa_fp16_overflow 0
		.amdhsa_tg_split 0
		.amdhsa_exception_fp_ieee_invalid_op 0
		.amdhsa_exception_fp_denorm_src 0
		.amdhsa_exception_fp_ieee_div_zero 0
		.amdhsa_exception_fp_ieee_overflow 0
		.amdhsa_exception_fp_ieee_underflow 0
		.amdhsa_exception_fp_ieee_inexact 0
		.amdhsa_exception_int_div_zero 0
	.end_amdhsa_kernel

amdhsa.kernels:
  - .agpr_count:     0
    .args:
      - .offset:         0
        .size:           192
        .value_kind:     by_value
      - .offset:         192
        .size:           4
        .value_kind:     hidden_block_count_x
      - .offset:         196
        .size:           4
        .value_kind:     hidden_block_count_y
      - .offset:         200
        .size:           4
        .value_kind:     hidden_block_count_z
      - .offset:         204
        .size:           2
        .value_kind:     hidden_group_size_x
      - .offset:         206
        .size:           2
        .value_kind:     hidden_group_size_y
      - .offset:         208
        .size:           2
        .value_kind:     hidden_group_size_z
      - .offset:         210
        .size:           2
        .value_kind:     hidden_remainder_x
      - .offset:         212
        .size:           2
        .value_kind:     hidden_remainder_y
      - .offset:         214
        .size:           2
        .value_kind:     hidden_remainder_z
      - .offset:         232
        .size:           8
        .value_kind:     hidden_global_offset_x
      - .offset:         240
        .size:           8
        .value_kind:     hidden_global_offset_y
      - .offset:         248
        .size:           8
        .value_kind:     hidden_global_offset_z
      - .offset:         256
        .size:           2
        .value_kind:     hidden_grid_dims
      - .offset:         280
        .size:           8
        .value_kind:     hidden_multigrid_sync_arg
      - .offset:         312
        .size:           4
        .value_kind:     hidden_dynamic_lds_size
    .group_segment_fixed_size: 0
    .kernarg_segment_align: 8
    .kernarg_segment_size: 448
    .language:       OpenCL C
    .language_version:
      - 2
      - 0
    .max_flat_workgroup_size: 512
    .name:           _ZN2mk4megaENS_6ParamsE
    .private_segment_fixed_size: 0
    .sgpr_count:     108
    .sgpr_spill_count: 154
    .symbol:         _ZN2mk4megaENS_6ParamsE.kd
    .uniform_work_group_size: 1
    .uses_dynamic_stack: false
    .vgpr_count:     256
    .vgpr_spill_count: 0
    .wavefront_size: 64
